# Fourier-2 prompt units remapped so each XCD shares 4 row tiles x 8 (b,g)
# baseline (speedup 1.0000x reference)
.LBB0_719:
	v_mov_b32_e32 v9, v210
	s_cmp_lt_i32 s2, 1
	v_readfirstlane_b32 s4, v9
	s_movk_i32 s77, 0x2000
	s_mov_b32 s91, 0x10000
	s_cbranch_scc1 .LBB0_737
	s_bfe_u32 s0, s21, 0x30002
	s_lshl_b32 s0, s0, 4
	s_lshr_b32 s1, s21, 5
	s_lshl_b32 s1, s1, 2
	s_and_b32 s21, s21, 3
	s_or_b32 s21, s21, s1
	s_or_b32 s21, s21, s0
	v_lshlrev_b32_e32 v0, 4, v9
	v_add_u32_e32 v1, 0x2000, v0
	v_ashrrev_i32_e32 v2, 31, v1
	v_lshrrev_b32_e32 v2, 22, v2
	v_add_u32_e32 v2, v1, v2
	v_ashrrev_i32_e32 v8, 10, v2
	v_mul_i32_i24_e32 v2, 0x400, v8
	v_sub_u32_e32 v1, v1, v2
	v_lshrrev_b32_e32 v2, 4, v1
	v_bitop3_b32 v1, v2, v1, 32 bitop3:0x6c
	v_ashrrev_i32_e32 v2, 31, v1
	v_readlane_b32 s0, v255, 22
	v_lshrrev_b32_e32 v2, 26, v2
	v_readlane_b32 s1, v255, 23
	s_add_u32 s26, s0, 0xe900000
	v_add_u32_e32 v2, v1, v2
	v_lshlrev_b32_e32 v3, 3, v8
	s_addc_u32 s27, s1, 0
	s_ashr_i32 s6, s4, 6
	v_ashrrev_i32_e32 v10, 6, v2
	v_and_b32_e32 v3, -16, v3
	s_ashr_i32 s5, s4, 8
	s_lshl_b32 s28, s6, 10
	v_add_u32_e32 v3, v10, v3
	s_add_u32 s29, s0, 0x25900000
	v_and_b32_e32 v4, 3, v10
	s_mov_b32 s0, 0x1ffe0
	v_lshrrev_b32_e32 v5, 2, v3
	v_lshlrev_b32_e32 v6, 1, v3
	v_and_b32_e32 v2, 0xc0, v2
	v_and_or_b32 v4, v3, s0, v4
	v_and_b32_e32 v5, 4, v5
	v_and_b32_e32 v6, 24, v6
	v_sub_u32_e32 v1, v1, v2
	v_or3_b32 v4, v4, v5, v6
	v_lshlrev_b32_e32 v5, 5, v8
	v_ashrrev_i16_sdwa v1, v217, sext(v1) dst_sel:DWORD dst_unused:UNUSED_PAD src0_sel:DWORD src1_sel:BYTE_0
	v_and_b32_e32 v5, 32, v5
	v_bfe_i32 v11, v1, 0, 16
	v_add_lshl_u32 v1, v5, v11, 1
	v_lshl_add_u32 v128, v4, 15, v1
	v_lshl_add_u32 v130, v3, 14, v1
	v_bfe_i32 v1, v9, 27, 1
	v_lshrrev_b32_e32 v1, 22, v1
	v_add_u32_e32 v1, v0, v1
	v_and_b32_e32 v1, 0xfffffc00, v1
	v_sub_u32_e32 v0, v0, v1
	v_lshrrev_b32_e32 v1, 4, v0
	v_ashrrev_i32_e32 v2, 31, v9
	v_bitop3_b32 v0, v1, v0, 32 bitop3:0x6c
	v_lshrrev_b32_e32 v2, 26, v2
	v_ashrrev_i32_e32 v1, 31, v0
	v_add_u32_e32 v2, v9, v2
	v_lshrrev_b32_e32 v1, 26, v1
	v_ashrrev_i32_e32 v13, 6, v2
	v_add_u32_e32 v1, v0, v1
	v_lshlrev_b32_e32 v2, 3, v13
	v_ashrrev_i32_e32 v12, 6, v1
	v_and_b32_e32 v2, -16, v2
	v_add_u32_e32 v2, v12, v2
	v_and_b32_e32 v3, 3, v12
	s_addc_u32 s30, s1, 0
	v_and_or_b32 v3, v2, s0, v3
	s_ashr_i32 s0, s21, 31
	s_lshr_b32 s0, s0, 28
	s_add_i32 s7, s21, s0
	s_and_b32 s0, s7, -16
	s_ashr_i32 s39, s7, 4
	s_sub_i32 s10, s21, s0
	s_ashr_i32 s11, s10, 31
	s_ashr_i32 s7, s7, 6
	s_lshl_b32 s8, s39, 9
	s_lshl_b64 s[0:1], s[10:11], 22
	s_and_b32 s8, s8, 0x600
	s_ashr_i32 s9, s7, 31
	v_lshrrev_b32_e32 v4, 2, v2
	v_lshlrev_b32_e32 v5, 1, v2
	v_and_b32_e32 v1, 0xc0, v1
	s_add_u32 s8, s8, s7
	v_and_b32_e32 v4, 4, v4
	v_and_b32_e32 v5, 24, v5
	v_sub_u32_e32 v0, v0, v1
	s_addc_u32 s9, 0, s9
	v_or3_b32 v3, v3, v4, v5
	v_lshlrev_b32_e32 v4, 5, v13
	v_ashrrev_i16_sdwa v0, v217, sext(v0) dst_sel:DWORD dst_unused:UNUSED_PAD src0_sel:DWORD src1_sel:BYTE_0
	s_lshl_b64 s[8:9], s[8:9], 14
	v_and_b32_e32 v4, 32, v4
	v_bfe_i32 v14, v0, 0, 16
	s_add_u32 s22, s29, s8
	v_add_lshl_u32 v0, v4, v14, 1
	s_addc_u32 s23, s30, s9
	s_add_i32 s31, s28, 0
	v_lshl_add_u32 v132, v3, 15, v0
	s_add_i32 m0, s31, 0x10000
	v_lshl_add_u32 v134, v2, 14, v0
	global_load_lds_dwordx4 v132, s[22:23]
	s_add_i32 m0, s31, 0x12000
	s_add_u32 s8, s22, 0x400000
	global_load_lds_dwordx4 v128, s[22:23]
	s_addc_u32 s9, s23, 0
	s_add_i32 m0, s31, 0x14000
	v_mov_b32_e32 v133, v177
	global_load_lds_dwordx4 v132, s[8:9]
	s_add_i32 m0, s31, 0x16000
	s_add_u32 s18, s26, s0
	global_load_lds_dwordx4 v128, s[8:9]
	s_addc_u32 s19, s27, s1
	s_add_i32 s8, s31, 0x2000
	s_mov_b32 m0, s31
	s_add_u32 s0, s18, 0x200000
	global_load_lds_dwordx4 v134, s[18:19]
	s_mov_b32 m0, s8
	s_addc_u32 s1, s19, 0
	s_add_i32 s9, s31, 0x4000
	global_load_lds_dwordx4 v130, s[18:19]
	s_mov_b32 m0, s9
	s_add_i32 s33, s31, 0x6000
	global_load_lds_dwordx4 v134, s[0:1]
	s_mov_b32 m0, s33
	v_mov_b32_e32 v129, v177
	global_load_lds_dwordx4 v130, s[0:1]
	v_mov_b32_e32 v135, v177
	v_mov_b32_e32 v131, v177
	s_cmp_eq_u32 s5, 1
	v_lshl_add_u64 v[6:7], s[22:23], 0, v[132:133]
	v_lshl_add_u64 v[4:5], s[22:23], 0, v[128:129]
	v_lshl_add_u64 v[0:1], s[18:19], 0, v[134:135]
	s_cselect_b64 s[0:1], -1, 0
	s_cmp_lg_u32 s5, 1
	v_lshl_add_u64 v[2:3], s[18:19], 0, v[130:131]
	s_cbranch_scc1 .LBB0_722
	s_barrier
